# transposed row-tile mapping in P8 and transposed-reversed in P10 (instead of plain reversal), rest as v10
# speedup vs baseline: 1.0102x; 1.0049x over previous
; #define LAS __attribute__((address_space(3)))
; #define PG8_BAR __builtin_amdgcn_s_barrier()
;     __device__ bool next(int i, Unit& u) const {
;     ...
;         int wgid = (int)L; { const int q = nwg / NXCD, r = nwg % NXCD, xcd = wgid % NXCD, off = wgid / NXCD; wgid = (xcd < r ? xcd * (q + 1) : r * (q + 1) + (xcd - r) * q) + off; }
;         const int nig = WGM * nN, gid = wgid / nig, fm = gid * WGM, gsz = (nM - fm) < WGM ? (nM - fm) : WGM;
;         const int pm = fm + ((wgid % nig) % gsz), pn = (wgid % nig) / gsz;
;         u.pm = pm; u.pn = pn;
;         if (mode == 0) { u.aoff = (size_t)pm * 256 * lda2; u.boff = (size_t)pn * 256 * ldb2; }
;         else if (mode == 3) { const int b = pm >> 2, h = pm & 3; u.aoff = (size_t)(b * 256) * lda2 + (size_t)h * 1024; u.boff = (size_t)pn * 256 * ldb2 + (size_t)h * 1024; }
;         else if (mode == 4) { const int b = pm >> 3, nt_ = pm & 7, h = pn; u.aoff = (size_t)(nt_ * 256) * lda2 + (size_t)h * 1024; u.boff = (size_t)(b * 256) * ldb2 + (size_t)(2048 + h * 512) * 2; }
;         else if (mode == 5) { const int b = pm >> 5; u.aoff = (size_t)pm * 256 * lda2; u.boff = (size_t)(b * 1024 + pn * 256) * ldb2; }
;         else { const int b = pm >> 5; u.aoff = (size_t)pm * 256 * lda2; u.boff = (size_t)(b * 2048 + pn * 256) * ldb2; }
;         return true;
;     }
; template <class Epi>
; __device__ __forceinline__ void gemm_phase(LAS unsigned char* lds, const Gemm g, const Order& S, const Epi& E) {
;     const int tid = threadIdx.x, wid = __builtin_amdgcn_readfirstlane(tid >> 6), lane = tid & 63, wr = wid >> 2, wc = wid & 3, fr = lane & 15, fq = lane >> 4;
;     const int K = g.K, nt = K / BK;
;     unsigned voffA[2], voffB[2];
; #pragma unroll
;     for (int i = 0; i < 2; ++i) { int R, C; stage_rc(tid * 16 + i * 8192, R, C); const int Rb = Epi::PERM ? ((R & ~31) + perm32(R & 31)) : R;
;         voffA[i] = (unsigned)(R * g.lda + C) * 2u; voffB[i] = (unsigned)(Rb * g.ldb + C) * 2u; }
;     ...
;     const char* cA = (const char*)g.A + cur.aoff; const char* cB = (const char*)g.Bt + cur.boff;
;     PG8_STAGE(PG8_SB(0, 0), cB, voffB); PG8_STAGE(PG8_SB(0, 1), cB + hstepB, voffB); PG8_STAGE(PG8_SA(0, 0), cA, voffA); PG8_STAGE(PG8_SA(0, 1), cA + hstepA, voffA);
;     if (wr == 1) PG8_BAR;
.LBB0_851:
	s_cmp_lt_i32 s74, 9
	s_cselect_b64 s[20:21], -1, 0
	s_and_b64 s[0:1], s[20:21], s[24:25]
	s_andn2_b64 vcc, exec, s[0:1]
	s_cbranch_vccnz .LBB0_880
	s_load_dword s0, s[96:97], 0xc0
	v_readlane_b32 s3, v250, 41
	v_readfirstlane_b32 s5, v206
	s_waitcnt vmcnt(0) lgkmcnt(0)
	v_cvt_f32_u32_e32 v0, s0
	s_sub_i32 s1, 0, s0
	v_rcp_iflag_f32_e32 v0, v0
	s_nop 0
	v_mul_f32_e32 v0, 0x4f7ffffe, v0
	v_cvt_u32_f32_e32 v0, v0
	s_nop 0
	v_readfirstlane_b32 s2, v0
	s_mul_i32 s1, s1, s2
	s_mul_hi_u32 s1, s2, s1
	s_add_i32 s2, s2, s1
	s_mul_hi_u32 s1, s3, s2
	s_mul_i32 s1, s1, s0
	s_sub_i32 s1, s3, s1
	s_sub_i32 s2, s1, s0
	s_cmp_ge_u32 s1, s0
	s_cselect_b32 s1, s2, s1
	s_sub_i32 s2, s1, s0
	s_cmp_ge_u32 s1, s0
	s_cselect_b32 s1, s2, s1
	s_cmpk_gt_i32 s1, 0x15ff
	s_cbranch_scc1 .LBB0_880
	v_lshrrev_b32_e32 v0, 5, v206
	v_lshrrev_b32_e32 v2, 1, v206
	v_and_b32_e32 v0, 4, v0
	v_bfe_u32 v1, v206, 2, 2
	v_and_b32_e32 v11, 24, v2
	v_or3_b32 v0, v0, v1, v11
	v_lshlrev_b32_e32 v1, 4, v206
	v_add_u32_e32 v8, 0x2000, v1
	v_lshrrev_b32_e32 v2, 7, v8
	s_movk_i32 s4, 0xe0
	v_and_b32_e32 v4, 32, v206
	v_and_or_b32 v3, v2, s4, v0
	v_bitop3_b32 v9, v1, v4, 48 bitop3:0x6c
	v_and_b32_e32 v10, 64, v206
	v_bfe_u32 v12, v206, 2, 4
	s_movk_i32 s4, 0xf0
	v_or_b32_e32 v1, v9, v10
	v_and_or_b32 v2, v2, s4, v12
	s_add_u32 s2, s72, 0x2c400000
	v_lshl_or_b32 v146, v2, 12, v1
	v_lshrrev_b32_e32 v2, 3, v206
	s_movk_i32 s4, 0x60
	s_addc_u32 s3, s73, 0
	v_and_or_b32 v0, v2, s4, v0
	s_movk_i32 s4, 0x70
	s_ashr_i32 s60, s1, 31
	v_lshl_or_b32 v148, v0, 12, v1
	v_and_or_b32 v0, v2, s4, v12
	s_lshr_b32 s4, s60, 29
	s_add_i32 s4, s1, s4
	s_lshr_b32 s6, s5, 6
	s_ashr_i32 s7, s4, 3
	s_and_b32 s4, s4, -8
	s_lshr_b32 s33, s5, 8
	s_lshl_b32 s43, s6, 10
	s_sub_i32 s4, s1, s4
	s_cmp_lt_i32 s4, 0
	s_movk_i32 s61, 0x2c1
	s_cselect_b32 s8, s61, 0x2c0
	s_mul_i32 s4, s4, s8
	s_add_i32 s4, s4, s7
	s_mul_hi_i32 s7, s4, 0x2e8ba2e9
	s_lshr_b32 s8, s7, 31
	s_ashr_i32 s7, s7, 5
	s_add_i32 s7, s7, s8
	s_lshl_b32 s8, s7, 2
	s_mulk_i32 s7, 0xb0
	s_sub_i32 s7, s4, s7
	s_bfe_u32 s4, s7, 0x2001d
	s_add_i32 s9, s7, s4
	s_sext_i32_i16 s4, s9
	s_and_b32 s9, s9, 0xfffc
	s_sub_i32 s7, s7, s9
	s_sext_i32_i16 s7, s7
	s_lshr_b32 s4, s4, 2
	s_add_i32 s58, s8, s7
	s_and_b32 s98, s58, 15
	s_lshl_b32 s98, s98, 3
	s_lshr_b32 s99, s58, 4
	s_add_i32 s58, s98, s99
	s_ashr_i32 s59, s58, 31
	s_bfe_i64 s[10:11], s[4:5], 0x100000
	s_lshl_b64 s[8:9], s[58:59], 20
	s_lshl_b64 s[10:11], s[10:11], 20
	s_add_u32 s16, s2, s10
	s_addc_u32 s17, s3, s11
	s_add_i32 s62, s43, 0
	s_add_i32 m0, s62, 0x10000
	v_lshl_or_b32 v144, v3, 12, v1
	global_load_lds_dwordx4 v148, s[16:17]
	s_add_i32 m0, s62, 0x12000
	s_add_u32 s10, s16, 0x80000
	global_load_lds_dwordx4 v144, s[16:17]
	s_addc_u32 s11, s17, 0
	s_add_i32 m0, s62, 0x14000
	v_lshl_or_b32 v150, v0, 12, v1
	global_load_lds_dwordx4 v148, s[10:11]
	s_add_i32 m0, s62, 0x16000
	s_add_u32 s14, s44, s8
	s_addc_u32 s15, s45, s9
	s_add_i32 s63, s62, 0x2000
	global_load_lds_dwordx4 v144, s[10:11]
	s_mov_b32 m0, s62
	s_add_u32 s8, s14, 0x80000
	global_load_lds_dwordx4 v150, s[14:15]
	s_mov_b32 m0, s63
	s_addc_u32 s9, s15, 0
	s_add_i32 s64, s62, 0x4000
	global_load_lds_dwordx4 v146, s[14:15]
	s_mov_b32 m0, s64
	s_add_i32 s65, s62, 0x6000
	global_load_lds_dwordx4 v150, s[8:9]
	s_mov_b32 m0, s65
	v_writelane_b32 v250, s78, 48
	global_load_lds_dwordx4 v146, s[8:9]
	v_mov_b32_e32 v149, 0
	v_writelane_b32 v250, s79, 49
	v_mov_b32_e32 v145, v149
	v_mov_b32_e32 v151, v149
	v_mov_b32_e32 v147, v149
	s_cmp_eq_u32 s33, 1
	v_writelane_b32 v250, s76, 44
	v_lshl_add_u64 v[6:7], s[16:17], 0, v[148:149]
	v_lshl_add_u64 v[4:5], s[16:17], 0, v[144:145]
	v_lshl_add_u64 v[0:1], s[14:15], 0, v[150:151]
	s_cselect_b64 s[24:25], -1, 0
	s_cmp_lg_u32 s33, 1
	v_lshl_add_u64 v[2:3], s[14:15], 0, v[146:147]
	v_writelane_b32 v250, s77, 45
	s_cbranch_scc1 .LBB0_855
	s_barrier

;     __device__ bool next(int i, Unit& u) const {
;     ...
;         int wgid = (int)L; { const int q = nwg / NXCD, r = nwg % NXCD, xcd = wgid % NXCD, off = wgid / NXCD; wgid = (xcd < r ? xcd * (q + 1) : r * (q + 1) + (xcd - r) * q) + off; }
;         const int nig = WGM * nN, gid = wgid / nig, fm = gid * WGM, gsz = (nM - fm) < WGM ? (nM - fm) : WGM;
;         const int pm = fm + ((wgid % nig) % gsz), pn = (wgid % nig) / gsz;
;         u.pm = pm; u.pn = pn;
;         if (mode == 0) { u.aoff = (size_t)pm * 256 * lda2; u.boff = (size_t)pn * 256 * ldb2; }
.LBB0_858:
	s_add_i32 s76, s76, 1
	s_mul_i32 s12, s76, s77
	s_mul_hi_u32 s13, s76, s0
	s_add_i32 s13, s13, s12
	s_mul_i32 s12, s76, s0
	s_add_u32 s18, s12, s1
	s_addc_u32 s19, s13, s60
	v_cmp_gt_i64_e32 vcc, s[18:19], v[162:163]
	v_cmp_lt_i64_e64 s[12:13], s[18:19], v[160:161]
	s_cbranch_vccnz .LBB0_860
	s_ashr_i32 s19, s18, 31
	s_lshr_b32 s19, s19, 29
	s_add_i32 s19, s18, s19
	s_ashr_i32 s46, s19, 3
	s_and_b32 s19, s19, -8
	s_sub_i32 s18, s18, s19
	s_cmp_lt_i32 s18, 0
	s_cselect_b32 s19, s61, 0x2c0
	s_mul_i32 s18, s18, s19
	s_add_i32 s18, s18, s46
	s_mul_hi_i32 s19, s18, 0x2e8ba2e9
	s_lshr_b32 s46, s19, 31
	s_ashr_i32 s19, s19, 5
	s_add_i32 s19, s19, s46
	s_lshl_b32 s47, s19, 2
	s_sub_i32 s46, 0x80, s47
	s_min_i32 s48, s46, 4
	s_abs_i32 s46, s48
	v_cvt_f32_u32_e32 v0, s46
	s_sub_i32 s50, 0, s46
	s_mulk_i32 s19, 0xb0
	s_sub_i32 s18, s18, s19
	v_rcp_iflag_f32_e32 v0, v0
	s_abs_i32 s19, s18
	s_xor_b32 s49, s18, s48
	s_ashr_i32 s49, s49, 31
	v_mul_f32_e32 v0, 0x4f7ffffe, v0
	v_cvt_u32_f32_e32 v0, v0
	s_nop 0
	v_readfirstlane_b32 s51, v0
	s_mul_i32 s50, s50, s51
	s_mul_hi_u32 s50, s51, s50
	s_add_i32 s51, s51, s50
	s_mul_hi_u32 s50, s19, s51
	s_mul_i32 s51, s50, s46
	s_sub_i32 s19, s19, s51
	s_add_i32 s52, s50, 1
	s_sub_i32 s51, s19, s46
	s_cmp_ge_u32 s19, s46
	s_cselect_b32 s50, s52, s50
	s_cselect_b32 s19, s51, s19
	s_add_i32 s51, s50, 1
	s_cmp_ge_u32 s19, s46
	s_cselect_b32 s19, s51, s50
	s_xor_b32 s19, s19, s49
	s_sub_i32 s46, s19, s49
	s_mul_i32 s19, s46, s48
	s_sub_i32 s18, s18, s19
	s_add_i32 s48, s47, s18
	s_and_b32 s98, s48, 15
	s_lshl_b32 s98, s98, 3
	s_lshr_b32 s99, s48, 4
	s_add_i32 s48, s98, s99
	s_ashr_i32 s49, s48, 31
	s_ashr_i32 s47, s46, 31
	s_lshl_b64 s[50:51], s[48:49], 20
	s_lshl_b64 s[52:53], s[46:47], 20

; #define LAS __attribute__((address_space(3)))
; #define PG8_BAR __builtin_amdgcn_s_barrier()
;     __device__ bool next(int i, Unit& u) const {
;     ...
;         int wgid = (int)L; { const int q = nwg / NXCD, r = nwg % NXCD, xcd = wgid % NXCD, off = wgid / NXCD; wgid = (xcd < r ? xcd * (q + 1) : r * (q + 1) + (xcd - r) * q) + off; }
;         const int nig = WGM * nN, gid = wgid / nig, fm = gid * WGM, gsz = (nM - fm) < WGM ? (nM - fm) : WGM;
;         const int pm = fm + ((wgid % nig) % gsz), pn = (wgid % nig) / gsz;
;         u.pm = pm; u.pn = pn;
;         if (mode == 0) { u.aoff = (size_t)pm * 256 * lda2; u.boff = (size_t)pn * 256 * ldb2; }
;         else if (mode == 3) { const int b = pm >> 2, h = pm & 3; u.aoff = (size_t)(b * 256) * lda2 + (size_t)h * 1024; u.boff = (size_t)pn * 256 * ldb2 + (size_t)h * 1024; }
;         else if (mode == 4) { const int b = pm >> 3, nt_ = pm & 7, h = pn; u.aoff = (size_t)(nt_ * 256) * lda2 + (size_t)h * 1024; u.boff = (size_t)(b * 256) * ldb2 + (size_t)(2048 + h * 512) * 2; }
;         else if (mode == 5) { const int b = pm >> 5; u.aoff = (size_t)pm * 256 * lda2; u.boff = (size_t)(b * 1024 + pn * 256) * ldb2; }
;         else { const int b = pm >> 5; u.aoff = (size_t)pm * 256 * lda2; u.boff = (size_t)(b * 2048 + pn * 256) * ldb2; }
;         return true;
;     }
; template <class Epi>
; __device__ __forceinline__ void gemm_phase(LAS unsigned char* lds, const Gemm g, const Order& S, const Epi& E) {
;     const int tid = threadIdx.x, wid = __builtin_amdgcn_readfirstlane(tid >> 6), lane = tid & 63, wr = wid >> 2, wc = wid & 3, fr = lane & 15, fq = lane >> 4;
;     const int K = g.K, nt = K / BK;
;     unsigned voffA[2], voffB[2];
; #pragma unroll
;     for (int i = 0; i < 2; ++i) { int R, C; stage_rc(tid * 16 + i * 8192, R, C); const int Rb = Epi::PERM ? ((R & ~31) + perm32(R & 31)) : R;
;         voffA[i] = (unsigned)(R * g.lda + C) * 2u; voffB[i] = (unsigned)(Rb * g.ldb + C) * 2u; }
;     ...
;     const char* cA = (const char*)g.A + cur.aoff; const char* cB = (const char*)g.Bt + cur.boff;
;     PG8_STAGE(PG8_SB(0, 0), cB, voffB); PG8_STAGE(PG8_SB(0, 1), cB + hstepB, voffB); PG8_STAGE(PG8_SA(0, 0), cA, voffA); PG8_STAGE(PG8_SA(0, 1), cA + hstepA, voffA);
;     if (wr == 1) PG8_BAR;
.LBB0_1011:
	s_add_u32 s3, s72, 0x14400000
	v_lshrrev_b32_e32 v3, 1, v206
	s_addc_u32 s33, s73, 0
	v_and_b32_e32 v10, 24, v3
	v_lshrrev_b32_e32 v3, 5, v206
	s_add_u32 s38, s72, 0x2f000000
	v_and_b32_e32 v3, 4, v3
	v_bfe_u32 v4, v206, 2, 2
	s_addc_u32 s39, s73, 0
	v_lshlrev_b32_e32 v0, 4, v206
	v_and_b32_e32 v1, 32, v206
	v_bfe_u32 v2, v206, 2, 4
	v_or3_b32 v3, v3, v4, v10
	v_lshrrev_b32_e32 v4, 3, v206
	s_movk_i32 s9, 0x70
	s_add_i32 s5, s8, s5
	v_bitop3_b32 v8, v0, v1, 48 bitop3:0x6c
	v_and_or_b32 v5, v4, s9, v2
	s_movk_i32 s9, 0x60
	v_add_u32_e32 v0, 0x2000, v0
	s_ashr_i32 s8, s5, 31
	v_and_or_b32 v4, v4, s9, v3
	v_lshrrev_b32_e32 v0, 7, v0
	s_movk_i32 s9, 0xf0
	s_lshr_b32 s8, s8, 27
	v_and_or_b32 v2, v0, s9, v2
	s_movk_i32 s9, 0xe0
	s_add_i32 s8, s5, s8
	v_and_or_b32 v0, v0, s9, v3
	s_ashr_i32 s9, s8, 5
	s_and_b32 s8, s8, 0xffe0
	s_sub_i32 s8, s5, s8
	s_bfe_i32 s5, s8, 0x80000
	s_bfe_u32 s5, s5, 0x2000d
	s_add_i32 s11, s8, s5
	s_bfe_i32 s5, s11, 0x80000
	s_and_b32 s11, s11, 0xfc
	s_sub_i32 s8, s8, s11
	s_lshl_b32 s9, s9, 2
	s_sext_i32_i16 s13, s5
	s_sext_i32_i8 s8, s8
	v_and_b32_e32 v9, 64, v206
	s_lshr_b32 s10, s12, 6
	s_add_i32 s55, s9, s8
	s_and_b32 s98, s55, 15
	s_lshl_b32 s98, s98, 3
	s_lshr_b32 s99, s55, 4
	s_add_i32 s55, s98, s99
	s_sub_i32 s55, 0x7f, s55
	s_ashr_i32 s8, s13, 2
	s_lshr_b32 s4, s12, 8
	v_or_b32_e32 v1, v8, v9
	s_lshl_b32 s40, s10, 10
	s_lshr_b32 s5, s13, 2
	s_mul_hi_i32 s9, s8, 0x2c0000
	s_mul_i32 s8, s8, 0x2c0000
	v_lshrrev_b32_e32 v1, 1, v1
	v_mul_u32_u24_e32 v4, 0x1600, v4
	s_add_u32 s34, s38, s8
	v_or_b32_e32 v4, v4, v1
	s_addc_u32 s35, s39, s9
	s_add_i32 s41, s40, 0
	v_lshlrev_b32_e32 v130, 1, v4
	v_mul_u32_u24_e32 v0, 0x1600, v0
	s_add_i32 m0, s41, 0x10000
	v_or_b32_e32 v0, v0, v1
	global_load_lds_dwordx4 v130, s[34:35]
	s_add_i32 m0, s41, 0x12000
	v_lshlrev_b32_e32 v134, 1, v0
	s_add_u32 s8, s34, 0x160000
	global_load_lds_dwordx4 v134, s[34:35]
	s_addc_u32 s9, s35, 0
	s_add_i32 m0, s41, 0x14000
	s_mul_i32 s14, s55, 0x2c0000
	global_load_lds_dwordx4 v130, s[8:9]
	s_add_i32 m0, s41, 0x16000
	v_mul_u32_u24_e32 v11, 0x1600, v5
	s_mul_hi_i32 s11, s55, 0x2c0000
	s_add_u32 s30, s3, s14
	v_or_b32_e32 v5, v1, v11
	v_mul_u32_u24_e32 v12, 0x1600, v2
	s_addc_u32 s31, s33, s11
	s_add_i32 s42, s41, 0x2000
	v_lshlrev_b32_e32 v128, 1, v5
	v_or_b32_e32 v2, v12, v1
	global_load_lds_dwordx4 v134, s[8:9]
	s_mov_b32 m0, s41
	s_add_u32 s8, s30, 0x160000
	v_lshlrev_b32_e32 v132, 1, v2
	global_load_lds_dwordx4 v128, s[30:31]
	s_mov_b32 m0, s42
	s_addc_u32 s9, s31, 0
	s_add_i32 s43, s41, 0x4000
	global_load_lds_dwordx4 v132, s[30:31]
	s_mov_b32 m0, s43
	s_add_i32 s46, s41, 0x6000
	global_load_lds_dwordx4 v128, s[8:9]
	s_mov_b32 m0, s46
	v_mov_b32_e32 v131, 0
	global_load_lds_dwordx4 v132, s[8:9]
	v_mov_b32_e32 v135, v131
	v_mov_b32_e32 v129, v131
	v_mov_b32_e32 v133, v131
	s_cmp_eq_u32 s4, 1
	s_mov_b32 s47, 0
	v_lshl_add_u64 v[6:7], s[34:35], 0, v[130:131]
	v_lshl_add_u64 v[4:5], s[34:35], 0, v[134:135]
	v_lshl_add_u64 v[0:1], s[30:31], 0, v[128:129]
	s_cselect_b64 s[8:9], -1, 0
	s_cmp_lg_u32 s4, 1
	v_lshl_add_u64 v[2:3], s[30:31], 0, v[132:133]
	s_cbranch_scc1 .LBB0_1013
	s_barrier

;     __device__ bool next(int i, Unit& u) const {
;     ...
;         int wgid = (int)L; { const int q = nwg / NXCD, r = nwg % NXCD, xcd = wgid % NXCD, off = wgid / NXCD; wgid = (xcd < r ? xcd * (q + 1) : r * (q + 1) + (xcd - r) * q) + off; }
;         const int nig = WGM * nN, gid = wgid / nig, fm = gid * WGM, gsz = (nM - fm) < WGM ? (nM - fm) : WGM;
;         const int pm = fm + ((wgid % nig) % gsz), pn = (wgid % nig) / gsz;
;         u.pm = pm; u.pn = pn;
;         if (mode == 0) { u.aoff = (size_t)pm * 256 * lda2; u.boff = (size_t)pn * 256 * ldb2; }
.LBB0_1021:
	s_ashr_i32 s22, s24, 3
	s_add_i32 s22, s26, s22
	s_ashr_i32 s23, s22, 31
	s_lshr_b32 s23, s23, 27
	s_add_i32 s23, s22, s23
	s_ashr_i32 s24, s23, 5
	s_lshl_b32 s24, s24, 2
	s_sub_i32 s25, 0x80, s24
	s_min_i32 s25, s25, 4
	s_abs_i32 s26, s25
	v_cvt_f32_u32_e32 v0, s26
	s_sub_i32 s28, 0, s26
	s_andn2_b32 s23, s23, 31
	s_sub_i32 s22, s22, s23
	v_rcp_iflag_f32_e32 v0, v0
	s_abs_i32 s23, s22
	s_xor_b32 s27, s22, s25
	s_ashr_i32 s27, s27, 31
	v_mul_f32_e32 v0, 0x4f7ffffe, v0
	v_cvt_u32_f32_e32 v0, v0
	s_nop 0
	v_readfirstlane_b32 s29, v0
	s_mul_i32 s28, s28, s29
	s_mul_hi_u32 s28, s29, s28
	s_add_i32 s29, s29, s28
	s_mul_hi_u32 s28, s23, s29
	s_mul_i32 s29, s28, s26
	s_sub_i32 s23, s23, s29
	s_add_i32 s36, s28, 1
	s_sub_i32 s29, s23, s26
	s_cmp_ge_u32 s23, s26
	s_cselect_b32 s28, s36, s28
	s_cselect_b32 s23, s29, s23
	s_add_i32 s29, s28, 1
	s_cmp_ge_u32 s23, s26
	s_cselect_b32 s23, s29, s28
	s_xor_b32 s23, s23, s27
	s_sub_i32 s53, s23, s27
	s_mul_i32 s23, s53, s25
	s_sub_i32 s22, s22, s23
	s_add_i32 s54, s24, s22
	s_and_b32 s98, s54, 15
	s_lshl_b32 s98, s98, 3
	s_lshr_b32 s99, s54, 4
	s_add_i32 s54, s98, s99
	s_sub_i32 s54, 0x7f, s54
	s_mul_hi_i32 s23, s54, 0x2c0000
	s_mul_i32 s22, s54, 0x2c0000
	s_mul_hi_i32 s25, s53, 0x2c0000
	s_mul_i32 s24, s53, 0x2c0000

; __global__ void __launch_bounds__(512) fwd_megakernel(Params p) {
	.amdhsa_kernel _Z14fwd_megakernel6Params
		.amdhsa_group_segment_fixed_size 0
		.amdhsa_private_segment_fixed_size 0
		.amdhsa_kernarg_size 448
		.amdhsa_user_sgpr_count 2
		.amdhsa_user_sgpr_dispatch_ptr 0
		.amdhsa_user_sgpr_queue_ptr 0
		.amdhsa_user_sgpr_kernarg_segment_ptr 1
		.amdhsa_user_sgpr_dispatch_id 0
		.amdhsa_user_sgpr_kernarg_preload_length 0
		.amdhsa_user_sgpr_kernarg_preload_offset 0
		.amdhsa_user_sgpr_private_segment_size 0
		.amdhsa_uses_dynamic_stack 0
		.amdhsa_enable_private_segment 0
		.amdhsa_system_sgpr_workgroup_id_x 1
		.amdhsa_system_sgpr_workgroup_id_y 0
		.amdhsa_system_sgpr_workgroup_id_z 0
		.amdhsa_system_sgpr_workgroup_info 0
		.amdhsa_system_vgpr_workitem_id 2
		.amdhsa_next_free_vgpr 251
		.amdhsa_next_free_sgpr 102
		.amdhsa_accum_offset 252
		.amdhsa_reserve_vcc 1
		.amdhsa_float_round_mode_32 0
		.amdhsa_float_round_mode_16_64 0
		.amdhsa_float_denorm_mode_32 3
		.amdhsa_float_denorm_mode_16_64 3
		.amdhsa_dx10_clamp 1
		.amdhsa_ieee_mode 1
		.amdhsa_fp16_overflow 0
		.amdhsa_tg_split 0
		.amdhsa_exception_fp_ieee_invalid_op 0
		.amdhsa_exception_fp_denorm_src 0
		.amdhsa_exception_fp_ieee_div_zero 0
		.amdhsa_exception_fp_ieee_overflow 0
		.amdhsa_exception_fp_ieee_underflow 0
		.amdhsa_exception_fp_ieee_inexact 0
		.amdhsa_exception_int_div_zero 0
	.end_amdhsa_kernel

; __global__ void __launch_bounds__(512) fwd_megakernel(Params p) {
amdhsa.kernels:
  - .agpr_count:     0
    .args:
      - .offset:         0
        .size:           192
        .value_kind:     by_value
      - .offset:         192
        .size:           4
        .value_kind:     hidden_block_count_x
      - .offset:         196
        .size:           4
        .value_kind:     hidden_block_count_y
      - .offset:         200
        .size:           4
        .value_kind:     hidden_block_count_z
      - .offset:         204
        .size:           2
        .value_kind:     hidden_group_size_x
      - .offset:         206
        .size:           2
        .value_kind:     hidden_group_size_y
      - .offset:         208
        .size:           2
        .value_kind:     hidden_group_size_z
      - .offset:         210
        .size:           2
        .value_kind:     hidden_remainder_x
      - .offset:         212
        .size:           2
        .value_kind:     hidden_remainder_y
      - .offset:         214
        .size:           2
        .value_kind:     hidden_remainder_z
      - .offset:         232
        .size:           8
        .value_kind:     hidden_global_offset_x
      - .offset:         240
        .size:           8
        .value_kind:     hidden_global_offset_y
      - .offset:         248
        .size:           8
        .value_kind:     hidden_global_offset_z
      - .offset:         256
        .size:           2
        .value_kind:     hidden_grid_dims
      - .offset:         280
        .size:           8
        .value_kind:     hidden_multigrid_sync_arg
      - .offset:         312
        .size:           4
        .value_kind:     hidden_dynamic_lds_size
    .group_segment_fixed_size: 0
    .kernarg_segment_align: 8
    .kernarg_segment_size: 448
    .language:       OpenCL C
    .language_version:
      - 2
      - 0
    .max_flat_workgroup_size: 512
    .name:           _Z14fwd_megakernel6Params
    .private_segment_fixed_size: 0
    .sgpr_count:     108
    .sgpr_spill_count: 55
    .symbol:         _Z14fwd_megakernel6Params.kd
    .uniform_work_group_size: 1
    .uses_dynamic_stack: false
    .vgpr_count:     251
    .vgpr_spill_count: 0
    .wavefront_size: 64
